# phase C compressed branch: per-head q/gate loads issued one head ahead
# baseline (speedup 1.0000x reference)
; #define MFMA16(a, b, c) __builtin_amdgcn_mfma_f32_16x16x32_bf16((a), (b), (c), 0, 0, 0)
; DI int my_tid() { int t = threadIdx.x; asm volatile("" : "+v"(t)); return t; }
; DI void nsa_wave(const Params& p, int layer, int b, int g, int t0, unsigned char* lds, bf16_t* ybase) {
;   const int lane = my_tid() & 63, qi = lane & 15, quad = lane >> 4;
;   const int t = t0 + qi, cur = t0 >> 6;
;   const long tok = (long)b * SEQ + t;
;   const int bg = b * 2 + g;
;   u32x2* lo = (u32x2*)lds + (my_tid() >> 6) * 1024 + lane;
;   const float mf_c = p.mfix()[layer * 4 + 0], mf_s = p.mfix()[layer * 4 + 1], mf_w = p.mfix()[layer * 4 + 2];
;   const bool on_c = mf_c > 60.f, on_s = mf_s > 60.f, on_w = mf_w > 60.f;
;   const float SC = 0.125f * 1.44269504089f;
;   const bf16_t* Kc = p.kc() + (long)bg * 128 * 64;
;   const bf16_t* Vc = p.vct() + (long)bg * 64 * 128;
;   f32x4 ph[8];
; #pragma unroll
;   for (int kt = 0; kt < 8; ++kt) ph[kt] = (f32x4){0.f, 0.f, 0.f, 0.f};
; #pragma unroll 1
;   for (int hh = 0; hh < 4; ++hh) {
;     const bf16_t* qp0 = p.nq() + ((long)(b * 8 + g * 4 + hh) * SEQ + t) * 64 + quad * 8;
;     const bf16x8 q0 = ld8(qp0), q1 = ld8(qp0 + 32); const float gt = p.ngate()[tok * 32 + g * 4 + hh];
;     f32x4 sc[8];
;     float mx = on_c ? -1e30f : mf_c;
; #pragma unroll
;     for (int kt = 0; kt < 8; ++kt) {
;       const bf16_t* kp = Kc + (long)(kt * 16 + qi) * 64 + quad * 8;
;       sc[kt] = MFMA16(ld8(kp), q0, ((f32x4){0.f, 0.f, 0.f, 0.f}));
;       sc[kt] = MFMA16(ld8(kp + 32), q1, sc[kt]);
;       sc[kt] = sc[kt] * SC;
;     }
;     if (on_c) {
; #pragma unroll
;       for (int kt = 0; kt < 8; ++kt)
; #pragma unroll
;         for (int r = 0; r < 4; ++r) { const int c = kt * 16 + quad * 4 + r; if (c < NCMP && 16 * c + 31 <= t) mx = fmaxf(mx, sc[kt][r]); }
; DI void phaseC(const Params& p0, int layer, unsigned char* lds, bool probe) {
;     ...
;     const int qi5 = it >> 5, qt = qi5 < 8 ? 15 - qi5 : qi5 - 8, bg = it & 31;
;     nsa_wave(p, layer, bg >> 1, bg & 1, qt * 128 + (my_tid() >> 6) * 16, lds, probe ? p.dummy() : p.nz());
.LBB0_706:
	s_lshr_b32 s0, s27, 1
	v_writelane_b32 v255, s0, 17
	s_lshl_b32 s0, s27, 17
	s_and_b32 s36, s0, 0x3c0000
	s_lshl_b32 s0, s27, 13
	s_and_b32 s8, s0, 0x3c000
	s_mov_b64 s[42:43], 0
	s_add_u32 s40, s92, s42
	s_addc_u32 s41, s93, s43
	s_ashr_i32 s0, s27, 5
	s_sub_i32 s1, 15, s0
	s_add_i32 s9, s0, -8
	v_mov_b32_e32 v0, v210
	s_cmp_lt_i32 s0, 8
	s_cselect_b32 s9, s1, s9
	v_mov_b32_e32 v243, v210
	s_and_b32 s26, s27, 31
	v_readlane_b32 s0, v255, 15
	v_and_b32_e32 v6, 64, v228
	v_ashrrev_i32_e32 v0, 2, v0
	v_mov_b32_e32 v2, v210
	v_readlane_b32 s1, v255, 16
	s_add_u32 s0, s40, s0
	v_cndmask_b32_e64 v4, 0, 1, s[2:3]
	v_xor_b32_e32 v5, 16, v228
	v_add_u32_e32 v240, 64, v6
	v_bfe_u32 v241, v243, 4, 2
	v_and_b32_e32 v6, -16, v0
	s_addc_u32 s1, s41, s1
	v_mov_b32_e32 v3, 0x1f671000
	v_xor_b32_e32 v7, 32, v228
	v_lshlrev_b32_e32 v132, 4, v4
	v_lshlrev_b32_e32 v4, 13, v4
	v_and_b32_e32 v242, 15, v243
	v_cmp_lt_i32_e32 vcc, v5, v240
	v_lshlrev_b32_e32 v136, 6, v241
	v_lshl_add_u32 v244, s9, 7, v6
	global_load_dwordx3 v[154:156], v3, s[0:1] offset:256
	v_or_b32_e32 v130, s8, v4
	v_lshlrev_b32_e32 v2, 7, v2
	v_and_b32_e32 v239, 63, v243
	v_cndmask_b32_e32 v4, v228, v5, vcc
	v_cmp_lt_i32_e32 vcc, v7, v240
	v_add_u32_e32 v12, 0x14f, v136
	v_or_b32_e32 v160, v244, v242
	s_lshl_b32 s0, s26, 14
	v_cndmask_b32_e32 v5, v228, v7, vcc
	v_and_b32_e32 v7, 0xffffe000, v2
	v_lshlrev_b32_e32 v8, 3, v239
	s_add_u32 s0, s40, s0
	v_cmp_gt_i32_e64 s[58:59], v12, v160
	v_add_u32_e32 v12, 0x24f, v136
	v_mov_b32_e32 v135, v1
	v_and_b32_e32 v134, 48, v243
	v_lshlrev_b32_e32 v0, 3, v241
	v_lshlrev_b32_e32 v175, 2, v4
	v_lshlrev_b32_e32 v159, 2, v5
	v_add3_u32 v157, 32, v7, v8
	v_or_b32_e32 v4, 31, v136
	v_or_b32_e32 v5, 47, v136
	v_or_b32_e32 v7, 63, v136
	s_addc_u32 s1, s41, 0
	v_cmp_gt_i32_e64 s[68:69], v12, v160
	v_or_b32_e32 v12, 0x31f, v136
	v_mov_b32_e32 v3, v1
	v_lshlrev_b32_e32 v2, 7, v242
	v_add_u32_e32 v8, 0x4f, v136
	v_or_b32_e32 v9, 0x11f, v136
	v_or_b32_e32 v13, 0x21f, v136
	v_cmp_gt_i32_e64 s[44:45], v4, v160
	v_cmp_gt_i32_e64 s[46:47], v5, v160
	v_cmp_gt_i32_e64 s[48:49], v7, v160
	v_lshl_add_u64 v[4:5], s[0:1], 0, v[134:135]
	v_lshl_add_u64 v[6:7], s[0:1], 0, v[0:1]
	s_mov_b64 s[0:1], 0x1f5f0000
	v_cmp_gt_i32_e64 s[70:71], v12, v160
	v_or_b32_e32 v12, 0x32f, v136
	v_or_b32_e32 v10, 0x12f, v136
	v_or_b32_e32 v11, 0x13f, v136
	v_or_b32_e32 v14, 0x22f, v136
	v_or_b32_e32 v15, 0x23f, v136
	v_cmp_gt_i32_e64 s[50:51], v8, v160
	v_cmp_gt_i32_e64 s[52:53], v9, v160
	v_cmp_gt_i32_e64 s[60:61], v13, v160
	v_lshl_add_u64 v[8:9], v[6:7], 0, s[0:1]
	v_lshl_add_u64 v[30:31], v[4:5], 0, v[2:3]
	s_mov_b64 s[0:1], 0x1f570000
	v_cmp_gt_i32_e64 s[72:73], v12, v160
	v_lshlrev_b32_e32 v12, 8, v242
	v_mov_b32_e32 v13, v1
	v_cmp_gt_i32_e64 s[54:55], v10, v160
	v_cmp_gt_i32_e64 s[56:57], v11, v160
	v_cmp_gt_i32_e64 s[62:63], v14, v160
	v_lshl_add_u64 v[10:11], v[30:31], 0, s[0:1]
	v_cmp_gt_i32_e64 s[66:67], v15, v160
	v_lshl_add_u64 v[112:113], v[8:9], 0, v[12:13]
	v_or_b32_e32 v14, 0x1000, v12
	v_mov_b32_e32 v15, v1
	v_or_b32_e32 v16, 0x2000, v12
	v_mov_b32_e32 v17, v1
	v_or_b32_e32 v12, 0x3000, v12
	s_mov_b64 s[0:1], 0x1f5f0040
	v_lshl_add_u64 v[68:69], v[8:9], 0, v[14:15]
	v_lshl_add_u64 v[72:73], v[8:9], 0, v[16:17]
	v_lshl_add_u64 v[84:85], v[8:9], 0, v[12:13]
	v_lshl_add_u64 v[8:9], v[6:7], 0, s[0:1]
	s_mov_b64 s[0:1], 0x1f5f0080
	v_lshl_add_u64 v[88:89], v[8:9], 0, v[14:15]
	v_lshl_add_u64 v[92:93], v[8:9], 0, v[16:17]
	v_lshl_add_u64 v[96:97], v[8:9], 0, v[12:13]
	v_lshl_add_u64 v[8:9], v[6:7], 0, s[0:1]
	s_mov_b64 s[0:1], 0x1f5f00c0
	v_lshl_add_u64 v[6:7], v[6:7], 0, s[0:1]
	s_mov_b32 s0, 0x1f571000
	v_add_co_u32_e32 v38, vcc, s0, v30
	s_mov_b32 s0, 0x1f572000
	s_nop 0
	v_addc_co_u32_e32 v39, vcc, 0, v31, vcc
	v_add_co_u32_e32 v42, vcc, s0, v30
	s_mov_b32 s0, 0x1f573000
	s_nop 0
	v_addc_co_u32_e32 v43, vcc, 0, v31, vcc
	v_add_co_u32_e32 v62, vcc, s0, v30
	v_lshl_add_u64 v[100:101], v[8:9], 0, v[14:15]
	v_lshl_add_u64 v[104:105], v[8:9], 0, v[16:17]
	v_lshl_add_u64 v[116:117], v[8:9], 0, v[12:13]
	v_lshl_add_u64 v[120:121], v[6:7], 0, v[14:15]
	v_lshl_add_u64 v[124:125], v[6:7], 0, v[16:17]
	v_lshl_add_u64 v[128:129], v[6:7], 0, v[12:13]
	v_addc_co_u32_e32 v63, vcc, 0, v31, vcc
	global_load_dwordx4 v[2:5], v[10:11], off offset:64
	global_load_dwordx4 v[6:9], v[10:11], off offset:2048
	s_nop 0
	global_load_dwordx4 v[10:13], v[10:11], off offset:2112
	s_nop 0
	global_load_dwordx4 v[14:17], v[38:39], off
	global_load_dwordx4 v[18:21], v[38:39], off offset:64
	global_load_dwordx4 v[22:25], v[38:39], off offset:2048
	global_load_dwordx4 v[26:29], v[38:39], off offset:2112
	global_load_dwordx4 v[30:33], v[42:43], off offset:64
	global_load_dwordx4 v[34:37], v[42:43], off offset:2048
	s_nop 0
	global_load_dwordx4 v[38:41], v[38:39], off offset:-4096
	s_nop 0
	global_load_dwordx4 v[42:45], v[42:43], off offset:2112
	s_nop 0
	global_load_dwordx4 v[46:49], v[62:63], off offset:-4096
	global_load_dwordx4 v[50:53], v[62:63], off
	global_load_dwordx4 v[54:57], v[62:63], off offset:64
	global_load_dwordx4 v[58:61], v[62:63], off offset:2048
	s_nop 0
	global_load_dwordx4 v[62:65], v[62:63], off offset:2112
	s_nop 0
	global_load_dwordx2 v[66:67], v[68:69], off
	s_nop 0
	global_load_dwordx2 v[68:69], v[68:69], off offset:32
	s_nop 0
	global_load_dwordx2 v[70:71], v[72:73], off
	s_nop 0
	global_load_dwordx2 v[72:73], v[72:73], off offset:32
	s_nop 0
	global_load_dwordx2 v[74:75], v[112:113], off
	global_load_dwordx2 v[76:77], v[112:113], off offset:32
	global_load_dwordx2 v[78:79], v[112:113], off offset:64
	global_load_dwordx2 v[80:81], v[112:113], off offset:96
; #define MFMA16(a, b, c) __builtin_amdgcn_mfma_f32_16x16x32_bf16((a), (b), (c), 0, 0, 0)
; DI void nsa_wave(const Params& p, int layer, int b, int g, int t0, unsigned char* lds, bf16_t* ybase) {
;     ...
;   f32x4 ph[8];
; #pragma unroll
;   for (int kt = 0; kt < 8; ++kt) ph[kt] = (f32x4){0.f, 0.f, 0.f, 0.f};
; #pragma unroll 1
;   for (int hh = 0; hh < 4; ++hh) {
;     const bf16_t* qp0 = p.nq() + ((long)(b * 8 + g * 4 + hh) * SEQ + t) * 64 + quad * 8;
;     const bf16x8 q0 = ld8(qp0), q1 = ld8(qp0 + 32); const float gt = p.ngate()[tok * 32 + g * 4 + hh];
;     f32x4 sc[8];
;     float mx = on_c ? -1e30f : mf_c;
; #pragma unroll
;     for (int kt = 0; kt < 8; ++kt) {
;       const bf16_t* kp = Kc + (long)(kt * 16 + qi) * 64 + quad * 8;
;       sc[kt] = MFMA16(ld8(kp), q0, ((f32x4){0.f, 0.f, 0.f, 0.f}));
;       sc[kt] = MFMA16(ld8(kp + 32), q1, sc[kt]);
;       sc[kt] = sc[kt] * SC;
;     }
;     if (on_c) {
; #pragma unroll
;       for (int kt = 0; kt < 8; ++kt)
; #pragma unroll
;         for (int r = 0; r < 4; ++r) { const int c = kt * 16 + quad * 4 + r; if (c < NCMP && 16 * c + 31 <= t) mx = fmaxf(mx, sc[kt][r]); }
	global_load_dwordx2 v[82:83], v[84:85], off
	s_nop 0
	global_load_dwordx2 v[84:85], v[84:85], off offset:32
	s_nop 0
	global_load_dwordx2 v[86:87], v[88:89], off
	s_nop 0
	global_load_dwordx2 v[88:89], v[88:89], off offset:32
	s_nop 0
	global_load_dwordx2 v[90:91], v[92:93], off
	s_nop 0
	global_load_dwordx2 v[92:93], v[92:93], off offset:32
	s_nop 0
	global_load_dwordx2 v[94:95], v[96:97], off
	s_nop 0
	global_load_dwordx2 v[96:97], v[96:97], off offset:32
	s_nop 0
	global_load_dwordx2 v[98:99], v[100:101], off
	s_nop 0
	global_load_dwordx2 v[100:101], v[100:101], off offset:32
	s_nop 0
	global_load_dwordx2 v[102:103], v[104:105], off
	s_nop 0
	global_load_dwordx2 v[104:105], v[104:105], off offset:32
	s_nop 0
	global_load_dwordx2 v[106:107], v[112:113], off offset:128
	global_load_dwordx2 v[108:109], v[112:113], off offset:160
	global_load_dwordx2 v[110:111], v[112:113], off offset:192
	s_nop 0
	global_load_dwordx2 v[112:113], v[112:113], off offset:224
	s_nop 0
	global_load_dwordx2 v[114:115], v[116:117], off
	s_nop 0
	global_load_dwordx2 v[116:117], v[116:117], off offset:32
	s_nop 0
	global_load_dwordx2 v[118:119], v[120:121], off
	s_nop 0
	global_load_dwordx2 v[120:121], v[120:121], off offset:32
	s_nop 0
	global_load_dwordx2 v[122:123], v[124:125], off
	s_nop 0
	global_load_dwordx2 v[124:125], v[124:125], off offset:32
	s_nop 0
	global_load_dwordx2 v[126:127], v[128:129], off
	s_nop 0
	global_load_dwordx2 v[128:129], v[128:129], off offset:32
	v_or_b32_e32 v135, 0x33f, v136
	v_cmp_gt_i32_e64 s[74:75], v135, v160
	v_add_u32_e32 v135, 0x34f, v136
	v_cmp_gt_i32_e64 s[76:77], v135, v160
	v_or_b32_e32 v135, 0x41f, v136
	v_cmp_gt_i32_e64 s[78:79], v135, v160
	v_or_b32_e32 v135, 0x42f, v136
	v_cmp_gt_i32_e64 s[80:81], v135, v160
	v_or_b32_e32 v135, 0x43f, v136
	v_cmp_gt_i32_e64 s[82:83], v135, v160
	v_add_u32_e32 v135, 0x44f, v136
	v_cmp_gt_i32_e64 s[84:85], v135, v160
	v_or_b32_e32 v135, 0x51f, v136
	v_cmp_gt_i32_e64 s[86:87], v135, v160
	v_or_b32_e32 v135, 0x52f, v136
	v_mov_b32_e32 v131, v1
	v_cmp_gt_i32_e64 s[4:5], v135, v160
	v_or_b32_e32 v135, 0x53f, v136
	v_ashrrev_i32_e32 v161, 31, v160
	v_readlane_b32 s0, v254, 51
	v_mov_b32_e32 v133, v1
	v_cmp_gt_i32_e64 s[38:39], v135, v160
	v_add_u32_e32 v135, 0x54f, v136
	v_readlane_b32 s1, v254, 52
	v_lshl_add_u64 v[130:131], v[160:161], 0, v[130:131]
	s_waitcnt vmcnt(48)
	v_cmp_nlt_f32_e64 s[64:65], s25, v154
	v_cmp_gt_i32_e64 s[24:25], v135, v160
	v_or_b32_e32 v135, 0x61f, v136
	v_add_u32_e32 v137, 0x74f, v136
	v_lshl_add_u64 v[132:133], s[0:1], 0, v[132:133]
	v_lshlrev_b64 v[130:131], 7, v[130:131]
	v_cmp_gt_i32_e64 s[28:29], v135, v160
	v_or_b32_e32 v135, 0x62f, v136
	v_cmp_eq_u32_e32 vcc, 3, v241
	v_cmp_gt_i32_e64 s[8:9], v137, v160
	v_or_b32_e32 v174, 0x63f, v136
	v_add_u32_e32 v176, 0x64f, v136
	v_or_b32_e32 v177, 0x71f, v136
	v_or_b32_e32 v178, 0x72f, v136
	v_or_b32_e32 v179, 0x73f, v136
	v_lshlrev_b64 v[136:137], 7, v[160:161]
	v_lshl_add_u64 v[132:133], v[132:133], 0, s[36:37]
	v_or_b32_e32 v130, v130, v134
	v_mov_b32_e32 v166, 0
	s_mov_b32 s30, 0
	v_lshlrev_b32_e32 v158, 2, v241
	s_or_b64 s[96:97], vcc, s[8:9]
	v_cmp_gt_i32_e64 s[8:9], v135, v160
	v_lshl_add_u64 v[170:171], v[132:133], 0, v[136:137]
	v_lshl_add_u64 v[172:173], s[92:93], 0, v[130:131]
	v_mov_b32_e32 v167, v166
	v_mov_b32_e32 v168, v166
	v_mov_b32_e32 v169, v166
	v_mov_b32_e32 v162, v166
	v_mov_b32_e32 v163, v166
	v_mov_b32_e32 v164, v166
	v_mov_b32_e32 v165, v166
	v_mov_b32_e32 v148, v166
	v_mov_b32_e32 v149, v166
	v_mov_b32_e32 v146, v166
	v_mov_b32_e32 v147, v166
	v_mov_b32_e32 v152, v166
	v_mov_b32_e32 v153, v166
	v_mov_b32_e32 v150, v166
	v_mov_b32_e32 v151, v166
	v_mov_b32_e32 v140, v166
	v_mov_b32_e32 v141, v166
	v_mov_b32_e32 v138, v166
	v_mov_b32_e32 v139, v166
	v_mov_b32_e32 v144, v166
	v_mov_b32_e32 v145, v166
	v_mov_b32_e32 v142, v166
	v_mov_b32_e32 v143, v166
	v_mov_b32_e32 v132, v166
	v_mov_b32_e32 v133, v166
	v_mov_b32_e32 v130, v166
	v_mov_b32_e32 v131, v166
	v_mov_b32_e32 v136, v166
	v_mov_b32_e32 v137, v166
	v_mov_b32_e32 v134, v166
	v_mov_b32_e32 v135, v166
	v_cmp_gt_i32_e64 s[10:11], v174, v160
	v_cmp_gt_i32_e64 s[12:13], v176, v160
	v_cmp_gt_i32_e64 s[14:15], v177, v160
	v_cmp_gt_i32_e64 s[16:17], v178, v160
	v_cmp_gt_i32_e64 s[18:19], v179, v160
	s_mov_b64 s[20:21], 0xe170000
	v_lshl_add_u64 v[222:223], v[172:173], 0, s[42:43]
	v_lshl_add_u64 v[222:223], v[222:223], 0, s[20:21]
	global_load_dwordx4 v[216:219], v[222:223], off
	global_load_dwordx4 v[246:249], v[222:223], off offset:64
	v_lshl_add_u64 v[222:223], v[170:171], 0, s[42:43]
	global_load_dword v220, v[222:223], off
	s_branch .LBB0_708
; DI void nsa_wave(const Params& p, int layer, int b, int g, int t0, unsigned char* lds, bf16_t* ybase) {
;     ...
;     float sum = 0.f;
; #pragma unroll
;     for (int kt = 0; kt < 8; ++kt)
; #pragma unroll
;       for (int r = 0; r < 4; ++r) {
;         const int c = kt * 16 + quad * 4 + r;
;         const float e = (c < NCMP && 16 * c + 31 <= t) ? __builtin_amdgcn_exp2f(sc[kt][r] - mx) : 0.f;
;         sc[kt][r] = e; sum += e;
;       }
;     sum += __shfl_xor(sum, 16); sum += __shfl_xor(sum, 32);
;     const float inv = sum > 0.f ? 1.f / sum : 0.f;
.LBB0_707:
	v_sub_f32_e32 v206, v206, v245
	v_exp_f32_e32 v206, v206
	v_sub_f32_e32 v207, v207, v245
	v_exp_f32_e32 v207, v207
	v_sub_f32_e32 v204, v204, v245
	v_exp_f32_e32 v204, v204
	v_sub_f32_e32 v205, v205, v245
	v_exp_f32_e32 v205, v205
	v_sub_f32_e32 v202, v202, v245
	v_cndmask_b32_e64 v206, v206, 0, s[44:45]
	v_exp_f32_e32 v202, v202
	v_sub_f32_e32 v203, v203, v245
	v_add_f32_e32 v208, 0, v206
	v_cndmask_b32_e64 v207, v207, 0, s[46:47]
	v_exp_f32_e32 v203, v203
	v_sub_f32_e32 v200, v200, v245
	v_add_f32_e32 v208, v207, v208
	v_cndmask_b32_e64 v204, v204, 0, s[48:49]
	v_exp_f32_e32 v200, v200
	v_sub_f32_e32 v201, v201, v245
	v_add_f32_e32 v208, v204, v208
	v_cndmask_b32_e64 v205, v205, 0, s[50:51]
	v_exp_f32_e32 v201, v201
	v_sub_f32_e32 v198, v198, v245
	v_add_f32_e32 v208, v205, v208
	v_cndmask_b32_e64 v202, v202, 0, s[52:53]
	v_exp_f32_e32 v198, v198
	v_sub_f32_e32 v199, v199, v245
	v_add_f32_e32 v208, v202, v208
	v_cndmask_b32_e64 v203, v203, 0, s[54:55]
	v_exp_f32_e32 v199, v199
	v_sub_f32_e32 v196, v196, v245
	v_add_f32_e32 v208, v203, v208
	v_cndmask_b32_e64 v200, v200, 0, s[56:57]
	v_exp_f32_e32 v196, v196
	v_sub_f32_e32 v197, v197, v245
	v_add_f32_e32 v208, v200, v208
	v_cndmask_b32_e64 v201, v201, 0, s[58:59]
	v_exp_f32_e32 v197, v197
	v_sub_f32_e32 v194, v194, v245
	v_add_f32_e32 v208, v201, v208
	v_cndmask_b32_e64 v198, v198, 0, s[60:61]
	v_exp_f32_e32 v194, v194
	v_sub_f32_e32 v195, v195, v245
	v_add_f32_e32 v208, v198, v208
	v_cndmask_b32_e64 v199, v199, 0, s[62:63]
	v_exp_f32_e32 v195, v195
	v_sub_f32_e32 v192, v192, v245
	v_add_f32_e32 v208, v199, v208
	v_cndmask_b32_e64 v196, v196, 0, s[66:67]
	v_exp_f32_e32 v192, v192
	v_sub_f32_e32 v193, v193, v245
	v_add_f32_e32 v208, v196, v208
	v_cndmask_b32_e64 v197, v197, 0, s[68:69]
	v_exp_f32_e32 v193, v193
	v_sub_f32_e32 v190, v190, v245
	v_add_f32_e32 v208, v197, v208
	v_cndmask_b32_e64 v194, v194, 0, s[70:71]
	v_exp_f32_e32 v190, v190
	v_sub_f32_e32 v191, v191, v245
	v_add_f32_e32 v208, v194, v208
	v_cndmask_b32_e64 v195, v195, 0, s[72:73]
	v_exp_f32_e32 v191, v191
	v_sub_f32_e32 v188, v188, v245
	v_add_f32_e32 v208, v195, v208
	v_cndmask_b32_e64 v192, v192, 0, s[74:75]
	v_exp_f32_e32 v188, v188
	v_sub_f32_e32 v189, v189, v245
	v_add_f32_e32 v208, v192, v208
	v_cndmask_b32_e64 v193, v193, 0, s[76:77]
	v_exp_f32_e32 v189, v189
	v_sub_f32_e32 v186, v186, v245
	v_add_f32_e32 v208, v193, v208
	v_cndmask_b32_e64 v190, v190, 0, s[78:79]
	v_exp_f32_e32 v186, v186
	v_sub_f32_e32 v187, v187, v245
	v_add_f32_e32 v208, v190, v208
	v_cndmask_b32_e64 v191, v191, 0, s[80:81]
	v_exp_f32_e32 v187, v187
	v_sub_f32_e32 v184, v184, v245
	v_add_f32_e32 v208, v191, v208
	v_cndmask_b32_e64 v188, v188, 0, s[82:83]
	v_exp_f32_e32 v184, v184
	v_sub_f32_e32 v185, v185, v245
	v_add_f32_e32 v208, v188, v208
	v_cndmask_b32_e64 v189, v189, 0, s[84:85]
	v_exp_f32_e32 v185, v185
	v_sub_f32_e32 v182, v182, v245
	v_add_f32_e32 v209, v189, v208
	v_cndmask_b32_e64 v208, v186, 0, s[86:87]
	v_exp_f32_e32 v182, v182
	v_sub_f32_e32 v183, v183, v245
	v_add_f32_e32 v186, v208, v209
	v_cndmask_b32_e64 v209, v187, 0, s[4:5]
	v_exp_f32_e32 v183, v183
	v_sub_f32_e32 v180, v180, v245
	v_add_f32_e32 v186, v209, v186
	v_cndmask_b32_e64 v224, v184, 0, s[38:39]
	v_exp_f32_e32 v180, v180
	v_sub_f32_e32 v181, v181, v245
	v_add_f32_e32 v184, v224, v186
	v_cndmask_b32_e64 v225, v185, 0, s[24:25]
	v_exp_f32_e32 v181, v181
	v_sub_f32_e32 v178, v178, v245
	v_add_f32_e32 v184, v225, v184
	v_cndmask_b32_e64 v182, v182, 0, s[28:29]
	v_exp_f32_e32 v178, v178
	v_sub_f32_e32 v179, v179, v245
	v_add_f32_e32 v184, v182, v184
	v_cndmask_b32_e64 v183, v183, 0, s[8:9]
	v_exp_f32_e32 v179, v179
	v_sub_f32_e32 v176, v176, v245
	v_add_f32_e32 v184, v183, v184
	v_cndmask_b32_e64 v180, v180, 0, s[10:11]
	v_exp_f32_e32 v176, v176
	v_sub_f32_e32 v177, v177, v245
	v_add_f32_e32 v184, v180, v184
	v_cndmask_b32_e64 v181, v181, 0, s[12:13]
	v_exp_f32_e32 v177, v177
	v_add_f32_e32 v184, v181, v184
	v_cndmask_b32_e64 v226, v178, 0, s[14:15]
	v_add_f32_e32 v178, v226, v184
	v_cndmask_b32_e64 v227, v179, 0, s[16:17]
	v_add_f32_e32 v178, v227, v178
	v_cndmask_b32_e64 v246, v176, 0, s[18:19]
	v_add_f32_e32 v176, v246, v178
	v_cndmask_b32_e64 v247, v177, 0, s[96:97]
	v_add_f32_e32 v176, v247, v176
	ds_bpermute_b32 v177, v175, v176
	v_lshl_add_u64 v[170:171], v[170:171], 0, 4
	s_waitcnt lgkmcnt(0)
	v_add_f32_e32 v176, v176, v177
	ds_bpermute_b32 v177, v159, v176
	s_waitcnt lgkmcnt(0)
; #define MFMA16(a, b, c) __builtin_amdgcn_mfma_f32_16x16x32_bf16((a), (b), (c), 0, 0, 0)
; DI unsigned pk2(float lo, float hi) { f32x2 v = {lo, hi}; bf16x2_t b = __builtin_convertvector(v, bf16x2_t); return __builtin_bit_cast(unsigned, b); }
; DI void nsa_wave(const Params& p, int layer, int b, int g, int t0, unsigned char* lds, bf16_t* ybase) {
;     ...
;     const bf16_t* qp0 = p.nq() + ((long)(b * 8 + g * 4 + hh) * SEQ + t) * 64 + quad * 8;
;     const bf16x8 q0 = ld8(qp0), q1 = ld8(qp0 + 32); const float gt = p.ngate()[tok * 32 + g * 4 + hh];
;     ...
;     sum += __shfl_xor(sum, 16); sum += __shfl_xor(sum, 32);
;     const float inv = sum > 0.f ? 1.f / sum : 0.f;
; #pragma unroll
;     for (int kt = 0; kt < 8; ++kt) { sc[kt] = sc[kt] * inv; ph[kt] += sc[kt]; }
;     f32x4 oc[4];
; #pragma unroll
;     for (int dt = 0; dt < 4; ++dt) oc[dt] = (f32x4){0.f, 0.f, 0.f, 0.f};
; #pragma unroll
;     for (int mm = 0; mm < 4; ++mm) {
;       const bf16x8 pf = mk8((u32x4){pk2(sc[2 * mm][0], sc[2 * mm][1]), pk2(sc[2 * mm][2], sc[2 * mm][3]), pk2(sc[2 * mm + 1][0], sc[2 * mm + 1][1]), pk2(sc[2 * mm + 1][2], sc[2 * mm + 1][3])});
; #pragma unroll
;       for (int dt = 0; dt < 4; ++dt) {
;         const bf16_t* vp = Vc + (long)(dt * 16 + qi) * 128 + 32 * mm + quad * 4;
;         const u32x2 lo = *(const u32x2*)vp, hi = *(const u32x2*)(vp + 16);
;         oc[dt] = MFMA16(mk8((u32x4){lo[0], lo[1], hi[0], hi[1]}), pf, oc[dt]);
;       }
;     }
; #pragma unroll
;     for (int dt = 0; dt < 4; ++dt) { const f32x4 v = oc[dt] * gt; lo[(hh * 4 + dt) * 64] = (u32x2){pk2(v[0], v[1]), pk2(v[2], v[3])}; }
	v_add_f32_e32 v176, v176, v177
	v_div_scale_f32 v177, vcc, v176, v176, 1.0
	v_rcp_f32_e32 v178, v177
	v_cmp_lt_f32_e64 s[0:1], 0, v176
	v_fma_f32 v179, -v177, v178, 1.0
	v_fmac_f32_e32 v178, v179, v178
	v_div_scale_f32 v179, vcc, 1.0, v176, 1.0
	v_mul_f32_e32 v184, v179, v178
	v_fma_f32 v185, -v177, v184, v179
	v_fmac_f32_e32 v184, v185, v178
	v_fma_f32 v177, -v177, v184, v179
	v_div_fmas_f32 v177, v177, v178, v184
	v_div_fixup_f32 v176, v177, v176, 1.0
	v_cndmask_b32_e64 v248, 0, v176, s[0:1]
	v_pk_mul_f32 v[250:251], v[204:205], v[248:249] op_sel_hi:[1,0]
	v_pk_mul_f32 v[220:221], v[206:207], v[248:249] op_sel_hi:[1,0]
	v_pk_fma_f32 v[168:169], v[204:205], v[248:249], v[168:169] op_sel_hi:[1,0,1]
	v_pk_fma_f32 v[166:167], v[206:207], v[248:249], v[166:167] op_sel_hi:[1,0,1]
	v_pk_mul_f32 v[204:205], v[200:201], v[248:249] op_sel_hi:[1,0]
	v_pk_mul_f32 v[206:207], v[202:203], v[248:249] op_sel_hi:[1,0]
	v_pk_mul_f32 v[222:223], v[192:193], v[248:249] op_sel_hi:[1,0]
	v_pk_mul_f32 v[230:231], v[194:195], v[248:249] op_sel_hi:[1,0]
	v_pk_fma_f32 v[150:151], v[192:193], v[248:249], v[150:151] op_sel_hi:[1,0,1]
	v_pk_fma_f32 v[152:153], v[194:195], v[248:249], v[152:153] op_sel_hi:[1,0,1]
	v_cvt_pk_bf16_f32 v192, v220, v221
	v_cvt_pk_bf16_f32 v193, v250, v251
	v_cvt_pk_bf16_f32 v194, v206, v207
	v_cvt_pk_bf16_f32 v195, v204, v205
	v_pk_mul_f32 v[216:217], v[196:197], v[248:249] op_sel_hi:[1,0]
	v_pk_mul_f32 v[218:219], v[198:199], v[248:249] op_sel_hi:[1,0]
	v_pk_fma_f32 v[146:147], v[196:197], v[248:249], v[146:147] op_sel_hi:[1,0,1]
	v_pk_fma_f32 v[148:149], v[198:199], v[248:249], v[148:149] op_sel_hi:[1,0,1]
	v_mfma_f32_16x16x32_bf16 v[196:199], v[74:77], v[192:195], 0
	v_fma_f32 v164, v200, v248, v164
	v_fma_f32 v165, v201, v248, v165
	v_pk_fma_f32 v[162:163], v[202:203], v[248:249], v[162:163] op_sel_hi:[1,0,1]
	v_pk_mul_f32 v[184:185], v[188:189], v[248:249] op_sel_hi:[1,0]
	v_mfma_f32_16x16x32_bf16 v[200:203], v[66:69], v[192:195], 0
	v_fma_f32 v138, v188, v248, v138
	v_fma_f32 v139, v189, v248, v139
	v_pk_mul_f32 v[188:189], v[224:225], v[248:249] op_sel_hi:[1,0]
	v_pk_fma_f32 v[142:143], v[224:225], v[248:249], v[142:143] op_sel_hi:[1,0,1]
	v_pk_mul_f32 v[178:179], v[182:183], v[248:249] op_sel_hi:[1,0]
	v_pk_fma_f32 v[132:133], v[182:183], v[248:249], v[132:133] op_sel_hi:[1,0,1]
	v_pk_mul_f32 v[182:183], v[226:227], v[248:249] op_sel_hi:[1,0]
	v_pk_fma_f32 v[136:137], v[226:227], v[248:249], v[136:137] op_sel_hi:[1,0,1]
	v_mfma_f32_16x16x32_bf16 v[204:207], v[70:73], v[192:195], 0
	v_cvt_pk_bf16_f32 v224, v218, v219
	v_cvt_pk_bf16_f32 v225, v216, v217
	v_cvt_pk_bf16_f32 v226, v230, v231
	v_mfma_f32_16x16x32_bf16 v[192:195], v[82:85], v[192:195], 0
	v_cvt_pk_bf16_f32 v227, v222, v223
	v_pk_mul_f32 v[186:187], v[190:191], v[248:249] op_sel_hi:[1,0]
	v_pk_fma_f32 v[140:141], v[190:191], v[248:249], v[140:141] op_sel_hi:[1,0,1]
	v_mfma_f32_16x16x32_bf16 v[196:199], v[78:81], v[224:227], v[196:199]
	v_mul_f32_e64 v190, v208, v248
	v_mul_f32_e64 v191, v209, v248
	v_pk_mul_f32 v[176:177], v[180:181], v[248:249] op_sel_hi:[1,0]
	v_pk_fma_f32 v[130:131], v[180:181], v[248:249], v[130:131] op_sel_hi:[1,0,1]
	v_mfma_f32_16x16x32_bf16 v[200:203], v[86:89], v[224:227], v[200:203]
	v_mul_f32_e64 v180, v246, v248
	v_mul_f32_e64 v181, v247, v248
	s_mov_b64 s[0:1], 0x40000
	v_pk_fma_f32 v[144:145], v[208:209], v[248:249], v[144:145] op_sel_hi:[1,0,1]
	v_mfma_f32_16x16x32_bf16 v[204:207], v[90:93], v[224:227], v[204:207]
	v_fma_f32 v134, v246, v248, v134
	v_fma_f32 v135, v247, v248, v135
	v_lshl_add_u64 v[172:173], v[172:173], 0, s[0:1]
	v_mfma_f32_16x16x32_bf16 v[192:195], v[94:97], v[224:227], v[192:195]
	v_cvt_pk_bf16_f32 v224, v186, v187
	v_cvt_pk_bf16_f32 v225, v184, v185
	v_cvt_pk_bf16_f32 v226, v190, v191
	v_cvt_pk_bf16_f32 v227, v188, v189
	s_nop 1
	v_mfma_f32_16x16x32_bf16 v[184:187], v[106:109], v[224:227], v[196:199]
	v_mfma_f32_16x16x32_bf16 v[188:191], v[98:101], v[224:227], v[200:203]
	v_mfma_f32_16x16x32_bf16 v[196:199], v[102:105], v[224:227], v[204:207]
	s_nop 1
	v_cvt_pk_bf16_f32 v200, v178, v179
	v_cvt_pk_bf16_f32 v201, v176, v177
	v_cvt_pk_bf16_f32 v202, v182, v183
	v_cvt_pk_bf16_f32 v203, v180, v181
	v_mfma_f32_16x16x32_bf16 v[192:195], v[114:117], v[224:227], v[192:195]
	s_nop 0
	v_mfma_f32_16x16x32_bf16 v[176:179], v[110:113], v[200:203], v[184:187]
	v_mfma_f32_16x16x32_bf16 v[180:183], v[118:121], v[200:203], v[188:191]
	v_mfma_f32_16x16x32_bf16 v[184:187], v[122:125], v[200:203], v[196:199]
	s_waitcnt vmcnt(0)
	s_nop 4
	v_pk_mul_f32 v[178:179], v[174:175], v[178:179] op_sel_hi:[0,1]
	v_pk_mul_f32 v[176:177], v[174:175], v[176:177] op_sel_hi:[0,1]
	v_cvt_pk_bf16_f32 v176, v176, v177
	v_mfma_f32_16x16x32_bf16 v[188:191], v[126:129], v[200:203], v[192:195]
	s_cmpk_eq_i32 s30, 0x1800
	s_cbranch_scc1 .Lmy_cq_skip
	s_mov_b64 s[20:21], 0xe170000
	v_lshl_add_u64 v[222:223], v[172:173], 0, s[42:43]
	v_lshl_add_u64 v[222:223], v[222:223], 0, s[20:21]
	global_load_dwordx4 v[216:219], v[222:223], off
	global_load_dwordx4 v[246:249], v[222:223], off offset:64
	v_lshl_add_u64 v[222:223], v[170:171], 0, s[42:43]
	global_load_dword v220, v[222:223], off
; #define MFMA16(a, b, c) __builtin_amdgcn_mfma_f32_16x16x32_bf16((a), (b), (c), 0, 0, 0)
; DI unsigned pk2(float lo, float hi) { f32x2 v = {lo, hi}; bf16x2_t b = __builtin_convertvector(v, bf16x2_t); return __builtin_bit_cast(unsigned, b); }
; DI void nsa_wave(const Params& p, int layer, int b, int g, int t0, unsigned char* lds, bf16_t* ybase) {
;     ...
;   for (int hh = 0; hh < 4; ++hh) {
;     const bf16_t* qp0 = p.nq() + ((long)(b * 8 + g * 4 + hh) * SEQ + t) * 64 + quad * 8;
;     const bf16x8 q0 = ld8(qp0), q1 = ld8(qp0 + 32); const float gt = p.ngate()[tok * 32 + g * 4 + hh];
;     f32x4 sc[8];
;     float mx = on_c ? -1e30f : mf_c;
; #pragma unroll
;     for (int kt = 0; kt < 8; ++kt) {
;       const bf16_t* kp = Kc + (long)(kt * 16 + qi) * 64 + quad * 8;
;       sc[kt] = MFMA16(ld8(kp), q0, ((f32x4){0.f, 0.f, 0.f, 0.f}));
;       sc[kt] = MFMA16(ld8(kp + 32), q1, sc[kt]);
;       sc[kt] = sc[kt] * SC;
;     ...
;     for (int dt = 0; dt < 4; ++dt) { const f32x4 v = oc[dt] * gt; lo[(hh * 4 + dt) * 64] = (u32x2){pk2(v[0], v[1]), pk2(v[2], v[3])}; }
.Lmy_cq_skip:
	v_cvt_pk_bf16_f32 v177, v178, v179
	v_pk_mul_f32 v[178:179], v[174:175], v[182:183] op_sel_hi:[0,1]
	v_pk_mul_f32 v[180:181], v[174:175], v[180:181] op_sel_hi:[0,1]
	v_add_u32_e32 v192, s30, v157
	v_cvt_pk_bf16_f32 v180, v180, v181
	v_cvt_pk_bf16_f32 v181, v178, v179
	ds_write2st64_b64 v192, v[176:177], v[180:181] offset1:1
	v_pk_mul_f32 v[176:177], v[174:175], v[186:187] op_sel_hi:[0,1]
	v_pk_mul_f32 v[178:179], v[174:175], v[184:185] op_sel_hi:[0,1]
	v_cvt_pk_bf16_f32 v178, v178, v179
	v_cvt_pk_bf16_f32 v179, v176, v177
	v_pk_mul_f32 v[176:177], v[174:175], v[190:191] op_sel_hi:[0,1]
	v_pk_mul_f32 v[180:181], v[174:175], v[188:189] op_sel_hi:[0,1]
	s_addk_i32 s30, 0x800
	v_cvt_pk_bf16_f32 v180, v180, v181
	v_cvt_pk_bf16_f32 v181, v176, v177
	s_cmpk_eq_i32 s30, 0x2000
	ds_write2st64_b64 v192, v[178:179], v[180:181] offset0:2 offset1:3
	s_cbranch_scc1 .LBB0_712
.LBB0_708:
	s_mov_b64 s[0:1], -1
	s_andn2_b64 vcc, exec, s[64:65]
	s_waitcnt vmcnt(0)
	v_mov_b32_e32 v174, v220
	v_mfma_f32_16x16x32_bf16 v[180:183], v[38:41], v[216:219], 0
	s_waitcnt vmcnt(1)
	v_mfma_f32_16x16x32_bf16 v[180:183], v[2:5], v[246:249], v[180:183]
	s_nop 7
	v_pk_mul_f32 v[204:205], v[182:183], s[34:35] op_sel_hi:[1,0]
	v_pk_mul_f32 v[206:207], v[180:181], s[34:35] op_sel_hi:[1,0]
	v_mfma_f32_16x16x32_bf16 v[180:183], v[6:9], v[216:219], 0
	v_mfma_f32_16x16x32_bf16 v[180:183], v[10:13], v[246:249], v[180:183]
	s_nop 7
	v_pk_mul_f32 v[200:201], v[182:183], s[34:35] op_sel_hi:[1,0]
	v_pk_mul_f32 v[202:203], v[180:181], s[34:35] op_sel_hi:[1,0]
	v_mfma_f32_16x16x32_bf16 v[180:183], v[14:17], v[216:219], 0
	v_mfma_f32_16x16x32_bf16 v[180:183], v[18:21], v[246:249], v[180:183]
	s_nop 7
	v_pk_mul_f32 v[196:197], v[182:183], s[34:35] op_sel_hi:[1,0]
	v_pk_mul_f32 v[198:199], v[180:181], s[34:35] op_sel_hi:[1,0]
	v_mfma_f32_16x16x32_bf16 v[180:183], v[22:25], v[216:219], 0
	v_mfma_f32_16x16x32_bf16 v[180:183], v[26:29], v[246:249], v[180:183]
	s_nop 7
	v_pk_mul_f32 v[192:193], v[182:183], s[34:35] op_sel_hi:[1,0]
	v_pk_mul_f32 v[194:195], v[180:181], s[34:35] op_sel_hi:[1,0]
	v_mfma_f32_16x16x32_bf16 v[180:183], v[46:49], v[216:219], 0
	v_mfma_f32_16x16x32_bf16 v[180:183], v[30:33], v[246:249], v[180:183]
	s_nop 7
	v_pk_mul_f32 v[188:189], v[182:183], s[34:35] op_sel_hi:[1,0]
	v_pk_mul_f32 v[190:191], v[180:181], s[34:35] op_sel_hi:[1,0]
	v_mfma_f32_16x16x32_bf16 v[180:183], v[34:37], v[216:219], 0
	v_mfma_f32_16x16x32_bf16 v[180:183], v[42:45], v[246:249], v[180:183]
	s_nop 7
	v_pk_mul_f32 v[184:185], v[182:183], s[34:35] op_sel_hi:[1,0]
	v_pk_mul_f32 v[186:187], v[180:181], s[34:35] op_sel_hi:[1,0]
	v_mfma_f32_16x16x32_bf16 v[180:183], v[50:53], v[216:219], 0
	v_mfma_f32_16x16x32_bf16 v[224:227], v[54:57], v[246:249], v[180:183]
	v_mfma_f32_16x16x32_bf16 v[176:179], v[58:61], v[216:219], 0
	s_nop 6
	v_mul_f32_e64 v180, v226, s34
	v_mul_f32_e64 v181, v227, s34
	v_pk_mul_f32 v[182:183], v[224:225], s[34:35] op_sel_hi:[1,0]
	v_mfma_f32_16x16x32_bf16 v[224:227], v[62:65], v[246:249], v[176:179]
	s_nop 7
	v_pk_mul_f32 v[176:177], v[226:227], s[34:35] op_sel_hi:[1,0]
	v_pk_mul_f32 v[178:179], v[224:225], s[34:35] op_sel_hi:[1,0]
	s_cbranch_vccnz .LBB0_710
	s_mov_b64 s[0:1], 0
